# stacked small edits: conv item rebalance, static first queue item, relaxed store-drain waits at GEMM unit ends, select-item key-tile loads before the index-weight wait, deeper cbias GEMV
# speedup vs baseline: 1.0042x; 1.0042x over previous
.LBB0_26:
	v_readlane_b32 s26, v253, 33
	s_sub_i32 s27, s42, s26
	s_cmpk_lt_i32 s27, 0x800
	s_cbranch_scc1 .Lcv_plus
	s_cmpk_lt_i32 s27, 0x1000
	s_cbranch_scc0 .Lcv_extra
	s_cmp_eq_u32 s58, 0
	s_cbranch_scc1 .Lcv_plus
	s_cmpk_ge_i32 s26, 0x780
	s_cbranch_scc1 .LBB0_58
.Lcv_plus:
	s_addk_i32 s42, 0x800
	s_branch .Lcv_go
.Lcv_extra:
	s_cmpk_ge_i32 s26, 0x780
	s_cbranch_scc1 .LBB0_58
	s_cmpk_ge_i32 s27, 0x1380
	s_cbranch_scc1 .LBB0_58
	s_cmp_eq_u32 s58, 0
	s_cbranch_scc1 .Lcv_x0
	s_cmpk_lt_i32 s26, 0x400
	s_cbranch_scc1 .LBB0_58
	s_add_i32 s42, s26, 0x1380
	s_branch .Lcv_go
.Lcv_x0:
	s_cmpk_lt_i32 s26, 0x600
	s_cbranch_scc1 .LBB0_58
	s_movk_i32 s42, 0x1380
	s_cmpk_eq_i32 s27, 0x1000
	s_cselect_b32 s42, 0x1200, s42
	s_add_i32 s42, s42, s26
.Lcv_go:
	s_lshl_b32 s36, s42, 5
	s_lshl_b32 s38, s42, 3
	s_lshl_b32 s40, s42, 1
	s_add_i32 s40, s40, 0x7fffd900
	s_cmpk_gt_i32 s42, 0x1aff
	s_cbranch_scc1 .LBB0_58

.LBB0_83:
	v_add_co_u32_e32 v6, vcc, 0xffffc400, v6
	s_mov_b64 s[24:25], 0x1000
	s_nop 0
	v_addc_co_u32_e32 v7, vcc, -1, v7, vcc
	global_load_dword v64, v[6:7], off
	global_load_dword v65, v[6:7], off offset:1024
	global_load_dword v66, v[6:7], off offset:2048
	global_load_dword v67, v[6:7], off offset:3072
	ds_read_b128 v[128:131], v1
	v_lshl_add_u64 v[6:7], v[6:7], 0, s[24:25]
	global_load_dword v68, v[6:7], off
	global_load_dword v69, v[6:7], off offset:1024
	global_load_dword v70, v[6:7], off offset:2048
	global_load_dword v71, v[6:7], off offset:3072
	ds_read_b128 v[132:135], v1 offset:16
	v_lshl_add_u64 v[6:7], v[6:7], 0, s[24:25]
	global_load_dword v72, v[6:7], off
	global_load_dword v73, v[6:7], off offset:1024
	global_load_dword v74, v[6:7], off offset:2048
	global_load_dword v75, v[6:7], off offset:3072
	ds_read_b128 v[136:139], v1 offset:32
	v_lshl_add_u64 v[6:7], v[6:7], 0, s[24:25]
	global_load_dword v76, v[6:7], off
	global_load_dword v77, v[6:7], off offset:1024
	global_load_dword v78, v[6:7], off offset:2048
	global_load_dword v79, v[6:7], off offset:3072
	ds_read_b128 v[140:143], v1 offset:48
	v_lshl_add_u64 v[6:7], v[6:7], 0, s[24:25]
	global_load_dword v80, v[6:7], off
	global_load_dword v81, v[6:7], off offset:1024
	global_load_dword v82, v[6:7], off offset:2048
	global_load_dword v83, v[6:7], off offset:3072
	ds_read_b128 v[144:147], v1 offset:64
	v_lshl_add_u64 v[6:7], v[6:7], 0, s[24:25]
	global_load_dword v84, v[6:7], off
	global_load_dword v85, v[6:7], off offset:1024
	global_load_dword v86, v[6:7], off offset:2048
	global_load_dword v87, v[6:7], off offset:3072
	ds_read_b128 v[148:151], v1 offset:80
	v_lshl_add_u64 v[6:7], v[6:7], 0, s[24:25]
	global_load_dword v88, v[6:7], off
	global_load_dword v89, v[6:7], off offset:1024
	global_load_dword v90, v[6:7], off offset:2048
	global_load_dword v91, v[6:7], off offset:3072
	ds_read_b128 v[152:155], v1 offset:96
	v_lshl_add_u64 v[6:7], v[6:7], 0, s[24:25]
	global_load_dword v92, v[6:7], off
	global_load_dword v93, v[6:7], off offset:1024
	global_load_dword v94, v[6:7], off offset:2048
	global_load_dword v95, v[6:7], off offset:3072
	ds_read_b128 v[156:159], v1 offset:112
	v_lshl_add_u64 v[6:7], v[6:7], 0, s[24:25]
	global_load_dword v96, v[6:7], off
	global_load_dword v97, v[6:7], off offset:1024
	global_load_dword v98, v[6:7], off offset:2048
	global_load_dword v99, v[6:7], off offset:3072
	ds_read_b128 v[160:163], v1 offset:128
	v_lshl_add_u64 v[6:7], v[6:7], 0, s[24:25]
	global_load_dword v100, v[6:7], off
	global_load_dword v101, v[6:7], off offset:1024
	global_load_dword v102, v[6:7], off offset:2048
	global_load_dword v103, v[6:7], off offset:3072
	ds_read_b128 v[164:167], v1 offset:144
	v_lshl_add_u64 v[6:7], v[6:7], 0, s[24:25]
	global_load_dword v104, v[6:7], off
	global_load_dword v105, v[6:7], off offset:1024
	global_load_dword v106, v[6:7], off offset:2048
	global_load_dword v107, v[6:7], off offset:3072
	ds_read_b128 v[168:171], v1 offset:160
	v_lshl_add_u64 v[6:7], v[6:7], 0, s[24:25]
	global_load_dword v108, v[6:7], off
	global_load_dword v109, v[6:7], off offset:1024
	global_load_dword v110, v[6:7], off offset:2048
	global_load_dword v111, v[6:7], off offset:3072
	ds_read_b128 v[172:175], v1 offset:176
	v_lshl_add_u64 v[6:7], v[6:7], 0, s[24:25]
	global_load_dword v112, v[6:7], off
	global_load_dword v113, v[6:7], off offset:1024
	global_load_dword v114, v[6:7], off offset:2048
	global_load_dword v115, v[6:7], off offset:3072
	ds_read_b128 v[176:179], v1 offset:192
	v_lshl_add_u64 v[6:7], v[6:7], 0, s[24:25]
	global_load_dword v116, v[6:7], off
	global_load_dword v117, v[6:7], off offset:1024
	global_load_dword v118, v[6:7], off offset:2048
	global_load_dword v119, v[6:7], off offset:3072
	ds_read_b128 v[180:183], v1 offset:208
	v_lshl_add_u64 v[6:7], v[6:7], 0, s[24:25]
	global_load_dword v120, v[6:7], off
	global_load_dword v121, v[6:7], off offset:1024
	global_load_dword v122, v[6:7], off offset:2048
	global_load_dword v123, v[6:7], off offset:3072
	ds_read_b128 v[184:187], v1 offset:224
	v_lshl_add_u64 v[6:7], v[6:7], 0, s[24:25]
	s_waitcnt vmcnt(56) lgkmcnt(14)
	v_fmac_f32_e32 v12, v64, v128
	v_fmac_f32_e32 v12, v65, v129
	v_fmac_f32_e32 v12, v66, v130
	v_fmac_f32_e32 v12, v67, v131
	global_load_dword v124, v[6:7], off
	global_load_dword v125, v[6:7], off offset:1024
	global_load_dword v126, v[6:7], off offset:2048
	global_load_dword v127, v[6:7], off offset:3072
	ds_read_b128 v[188:191], v1 offset:240
	v_lshl_add_u64 v[6:7], v[6:7], 0, s[24:25]
	s_waitcnt vmcnt(56) lgkmcnt(14)
	v_pk_mul_f32 v[14:15], v[68:69], v[132:133]
	s_nop 0
	v_add_f32_e32 v12, v12, v14
	v_add_f32_e32 v12, v12, v15
	v_pk_mul_f32 v[14:15], v[70:71], v[134:135]
	s_nop 0
	v_add_f32_e32 v12, v12, v14
	v_add_f32_e32 v12, v12, v15
	global_load_dword v64, v[6:7], off
	global_load_dword v65, v[6:7], off offset:1024
	global_load_dword v66, v[6:7], off offset:2048
	global_load_dword v67, v[6:7], off offset:3072
	ds_read_b128 v[128:131], v1 offset:256
	v_lshl_add_u64 v[6:7], v[6:7], 0, s[24:25]
	s_waitcnt vmcnt(56) lgkmcnt(14)
	v_pk_mul_f32 v[14:15], v[72:73], v[136:137]
	s_nop 0
	v_add_f32_e32 v12, v12, v14
	v_add_f32_e32 v12, v12, v15
	v_pk_mul_f32 v[14:15], v[74:75], v[138:139]
	s_nop 0
	v_add_f32_e32 v12, v12, v14
	v_add_f32_e32 v12, v12, v15
	global_load_dword v68, v[6:7], off
	global_load_dword v69, v[6:7], off offset:1024
	global_load_dword v70, v[6:7], off offset:2048
	global_load_dword v71, v[6:7], off offset:3072
	ds_read_b128 v[132:135], v1 offset:272
	v_lshl_add_u64 v[6:7], v[6:7], 0, s[24:25]
	s_waitcnt vmcnt(56) lgkmcnt(14)
	v_pk_mul_f32 v[14:15], v[76:77], v[140:141]
	s_nop 0
	v_add_f32_e32 v12, v12, v14
	v_add_f32_e32 v12, v12, v15
	v_pk_mul_f32 v[14:15], v[78:79], v[142:143]
	s_nop 0
	v_add_f32_e32 v12, v12, v14
	v_add_f32_e32 v12, v12, v15
	global_load_dword v72, v[6:7], off
	global_load_dword v73, v[6:7], off offset:1024
	global_load_dword v74, v[6:7], off offset:2048
	global_load_dword v75, v[6:7], off offset:3072
	ds_read_b128 v[136:139], v1 offset:288
	v_lshl_add_u64 v[6:7], v[6:7], 0, s[24:25]
	s_waitcnt vmcnt(56) lgkmcnt(14)
	v_fmac_f32_e32 v12, v80, v144
	v_fmac_f32_e32 v12, v81, v145
	v_fmac_f32_e32 v12, v82, v146
	v_fmac_f32_e32 v12, v83, v147
	global_load_dword v76, v[6:7], off
	global_load_dword v77, v[6:7], off offset:1024
	global_load_dword v78, v[6:7], off offset:2048
	global_load_dword v79, v[6:7], off offset:3072
	ds_read_b128 v[140:143], v1 offset:304
	v_lshl_add_u64 v[6:7], v[6:7], 0, s[24:25]
	s_waitcnt vmcnt(56) lgkmcnt(14)
	v_pk_mul_f32 v[14:15], v[84:85], v[148:149]
	s_nop 0
	v_add_f32_e32 v12, v12, v14
	v_add_f32_e32 v12, v12, v15
	v_pk_mul_f32 v[14:15], v[86:87], v[150:151]
	s_nop 0
	v_add_f32_e32 v12, v12, v14
	v_add_f32_e32 v12, v12, v15
	global_load_dword v80, v[6:7], off
	global_load_dword v81, v[6:7], off offset:1024
	global_load_dword v82, v[6:7], off offset:2048
	global_load_dword v83, v[6:7], off offset:3072
	ds_read_b128 v[144:147], v1 offset:320
	v_lshl_add_u64 v[6:7], v[6:7], 0, s[24:25]
	s_waitcnt vmcnt(56) lgkmcnt(14)
	v_pk_mul_f32 v[14:15], v[88:89], v[152:153]
	s_nop 0
	v_add_f32_e32 v12, v12, v14
	v_add_f32_e32 v12, v12, v15
	v_pk_mul_f32 v[14:15], v[90:91], v[154:155]
	s_nop 0
	v_add_f32_e32 v12, v12, v14
	v_add_f32_e32 v12, v12, v15
	global_load_dword v84, v[6:7], off
	global_load_dword v85, v[6:7], off offset:1024
	global_load_dword v86, v[6:7], off offset:2048
	global_load_dword v87, v[6:7], off offset:3072
	ds_read_b128 v[148:151], v1 offset:336
	v_lshl_add_u64 v[6:7], v[6:7], 0, s[24:25]
	s_waitcnt vmcnt(56) lgkmcnt(14)
	v_pk_mul_f32 v[14:15], v[92:93], v[156:157]
	s_nop 0
	v_add_f32_e32 v12, v12, v14
	v_add_f32_e32 v12, v12, v15
	v_pk_mul_f32 v[14:15], v[94:95], v[158:159]
	s_nop 0
	v_add_f32_e32 v12, v12, v14
	v_add_f32_e32 v12, v12, v15
	global_load_dword v88, v[6:7], off
	global_load_dword v89, v[6:7], off offset:1024
	global_load_dword v90, v[6:7], off offset:2048
	global_load_dword v91, v[6:7], off offset:3072
	ds_read_b128 v[152:155], v1 offset:352
	v_lshl_add_u64 v[6:7], v[6:7], 0, s[24:25]
	s_waitcnt vmcnt(56) lgkmcnt(14)
	v_fmac_f32_e32 v12, v96, v160
	v_fmac_f32_e32 v12, v97, v161
	v_fmac_f32_e32 v12, v98, v162
	v_fmac_f32_e32 v12, v99, v163
	global_load_dword v92, v[6:7], off
	global_load_dword v93, v[6:7], off offset:1024
	global_load_dword v94, v[6:7], off offset:2048
	global_load_dword v95, v[6:7], off offset:3072
	ds_read_b128 v[156:159], v1 offset:368
	v_lshl_add_u64 v[6:7], v[6:7], 0, s[24:25]
	s_waitcnt vmcnt(56) lgkmcnt(14)
	v_pk_mul_f32 v[14:15], v[100:101], v[164:165]
	s_nop 0
	v_add_f32_e32 v12, v12, v14
	v_add_f32_e32 v12, v12, v15
	v_pk_mul_f32 v[14:15], v[102:103], v[166:167]
	s_nop 0
	v_add_f32_e32 v12, v12, v14
	v_add_f32_e32 v12, v12, v15
	global_load_dword v96, v[6:7], off
	global_load_dword v97, v[6:7], off offset:1024
	global_load_dword v98, v[6:7], off offset:2048
	global_load_dword v99, v[6:7], off offset:3072
	ds_read_b128 v[160:163], v1 offset:384
	v_lshl_add_u64 v[6:7], v[6:7], 0, s[24:25]
	s_waitcnt vmcnt(56) lgkmcnt(14)
	v_pk_mul_f32 v[14:15], v[104:105], v[168:169]
	s_nop 0
	v_add_f32_e32 v12, v12, v14
	v_add_f32_e32 v12, v12, v15
	v_pk_mul_f32 v[14:15], v[106:107], v[170:171]
	s_nop 0
	v_add_f32_e32 v12, v12, v14
	v_add_f32_e32 v12, v12, v15
	global_load_dword v100, v[6:7], off
	global_load_dword v101, v[6:7], off offset:1024
	global_load_dword v102, v[6:7], off offset:2048
	global_load_dword v103, v[6:7], off offset:3072
	ds_read_b128 v[164:167], v1 offset:400
	v_lshl_add_u64 v[6:7], v[6:7], 0, s[24:25]
	s_waitcnt vmcnt(56) lgkmcnt(14)
	v_pk_mul_f32 v[14:15], v[108:109], v[172:173]
	s_nop 0
	v_add_f32_e32 v12, v12, v14
	v_add_f32_e32 v12, v12, v15
	v_pk_mul_f32 v[14:15], v[110:111], v[174:175]
	s_nop 0
	v_add_f32_e32 v12, v12, v14
	v_add_f32_e32 v12, v12, v15
	global_load_dword v104, v[6:7], off
	global_load_dword v105, v[6:7], off offset:1024
	global_load_dword v106, v[6:7], off offset:2048
	global_load_dword v107, v[6:7], off offset:3072
	ds_read_b128 v[168:171], v1 offset:416
	v_lshl_add_u64 v[6:7], v[6:7], 0, s[24:25]
	s_waitcnt vmcnt(56) lgkmcnt(14)
	v_fmac_f32_e32 v12, v112, v176
	v_fmac_f32_e32 v12, v113, v177
	v_fmac_f32_e32 v12, v114, v178
	v_fmac_f32_e32 v12, v115, v179
	global_load_dword v108, v[6:7], off
	global_load_dword v109, v[6:7], off offset:1024
	global_load_dword v110, v[6:7], off offset:2048
	global_load_dword v111, v[6:7], off offset:3072
	ds_read_b128 v[172:175], v1 offset:432
	v_lshl_add_u64 v[6:7], v[6:7], 0, s[24:25]
	s_waitcnt vmcnt(56) lgkmcnt(14)
	v_pk_mul_f32 v[14:15], v[116:117], v[180:181]
	s_nop 0
	v_add_f32_e32 v12, v12, v14
	v_add_f32_e32 v12, v12, v15
	v_pk_mul_f32 v[14:15], v[118:119], v[182:183]
	s_nop 0
	v_add_f32_e32 v12, v12, v14
	v_add_f32_e32 v12, v12, v15
	global_load_dword v112, v[6:7], off
	global_load_dword v113, v[6:7], off offset:1024
	global_load_dword v114, v[6:7], off offset:2048
	global_load_dword v115, v[6:7], off offset:3072
	ds_read_b128 v[176:179], v1 offset:448
	v_lshl_add_u64 v[6:7], v[6:7], 0, s[24:25]
	s_waitcnt vmcnt(56) lgkmcnt(14)
	v_pk_mul_f32 v[14:15], v[120:121], v[184:185]
	s_nop 0
	v_add_f32_e32 v12, v12, v14
	v_add_f32_e32 v12, v12, v15
	v_pk_mul_f32 v[14:15], v[122:123], v[186:187]
	s_nop 0
	v_add_f32_e32 v12, v12, v14
	v_add_f32_e32 v12, v12, v15
	global_load_dword v116, v[6:7], off
	global_load_dword v117, v[6:7], off offset:1024
	global_load_dword v118, v[6:7], off offset:2048
	global_load_dword v119, v[6:7], off offset:3072
	ds_read_b128 v[180:183], v1 offset:464
	v_lshl_add_u64 v[6:7], v[6:7], 0, s[24:25]
	s_waitcnt vmcnt(56) lgkmcnt(14)
	v_pk_mul_f32 v[14:15], v[124:125], v[188:189]
	s_nop 0
	v_add_f32_e32 v12, v12, v14
	v_add_f32_e32 v12, v12, v15
	v_pk_mul_f32 v[14:15], v[126:127], v[190:191]
	s_nop 0
	v_add_f32_e32 v12, v12, v14
	v_add_f32_e32 v12, v12, v15
	global_load_dword v120, v[6:7], off
	global_load_dword v121, v[6:7], off offset:1024
	global_load_dword v122, v[6:7], off offset:2048
	global_load_dword v123, v[6:7], off offset:3072
	ds_read_b128 v[184:187], v1 offset:480
	v_lshl_add_u64 v[6:7], v[6:7], 0, s[24:25]
	s_waitcnt vmcnt(56) lgkmcnt(14)
	v_fmac_f32_e32 v12, v64, v128
	v_fmac_f32_e32 v12, v65, v129
	v_fmac_f32_e32 v12, v66, v130
	v_fmac_f32_e32 v12, v67, v131
	global_load_dword v124, v[6:7], off
	global_load_dword v125, v[6:7], off offset:1024
	global_load_dword v126, v[6:7], off offset:2048
	global_load_dword v127, v[6:7], off offset:3072
	ds_read_b128 v[188:191], v1 offset:496
	s_waitcnt vmcnt(56) lgkmcnt(14)
	v_pk_mul_f32 v[14:15], v[68:69], v[132:133]
	s_nop 0
	v_add_f32_e32 v12, v12, v14
	v_add_f32_e32 v12, v12, v15
	v_pk_mul_f32 v[14:15], v[70:71], v[134:135]
	s_nop 0
	v_add_f32_e32 v12, v12, v14
	v_add_f32_e32 v12, v12, v15
	s_waitcnt vmcnt(52) lgkmcnt(13)
	v_pk_mul_f32 v[14:15], v[72:73], v[136:137]
	s_nop 0
	v_add_f32_e32 v12, v12, v14
	v_add_f32_e32 v12, v12, v15
	v_pk_mul_f32 v[14:15], v[74:75], v[138:139]
	s_nop 0
	v_add_f32_e32 v12, v12, v14
	v_add_f32_e32 v12, v12, v15
	s_waitcnt vmcnt(48) lgkmcnt(12)
	v_pk_mul_f32 v[14:15], v[76:77], v[140:141]
	s_nop 0
	v_add_f32_e32 v12, v12, v14
	v_add_f32_e32 v12, v12, v15
	v_pk_mul_f32 v[14:15], v[78:79], v[142:143]
	s_nop 0
	v_add_f32_e32 v12, v12, v14
	v_add_f32_e32 v12, v12, v15
	s_waitcnt vmcnt(44) lgkmcnt(11)
	v_fmac_f32_e32 v12, v80, v144
	v_fmac_f32_e32 v12, v81, v145
	v_fmac_f32_e32 v12, v82, v146
	v_fmac_f32_e32 v12, v83, v147
	s_waitcnt vmcnt(40) lgkmcnt(10)
	v_pk_mul_f32 v[14:15], v[84:85], v[148:149]
	s_nop 0
	v_add_f32_e32 v12, v12, v14
	v_add_f32_e32 v12, v12, v15
	v_pk_mul_f32 v[14:15], v[86:87], v[150:151]
	s_nop 0
	v_add_f32_e32 v12, v12, v14
	v_add_f32_e32 v12, v12, v15
	s_waitcnt vmcnt(36) lgkmcnt(9)
	v_pk_mul_f32 v[14:15], v[88:89], v[152:153]
	s_nop 0
	v_add_f32_e32 v12, v12, v14
	v_add_f32_e32 v12, v12, v15
	v_pk_mul_f32 v[14:15], v[90:91], v[154:155]
	s_nop 0
	v_add_f32_e32 v12, v12, v14
	v_add_f32_e32 v12, v12, v15
	s_waitcnt vmcnt(32) lgkmcnt(8)
	v_pk_mul_f32 v[14:15], v[92:93], v[156:157]
	s_nop 0
	v_add_f32_e32 v12, v12, v14
	v_add_f32_e32 v12, v12, v15
	v_pk_mul_f32 v[14:15], v[94:95], v[158:159]
	s_nop 0
	v_add_f32_e32 v12, v12, v14
	v_add_f32_e32 v12, v12, v15
	s_waitcnt vmcnt(28) lgkmcnt(7)
	v_fmac_f32_e32 v12, v96, v160
	v_fmac_f32_e32 v12, v97, v161
	v_fmac_f32_e32 v12, v98, v162
	v_fmac_f32_e32 v12, v99, v163
	s_waitcnt vmcnt(24) lgkmcnt(6)
	v_pk_mul_f32 v[14:15], v[100:101], v[164:165]
	s_nop 0
	v_add_f32_e32 v12, v12, v14
	v_add_f32_e32 v12, v12, v15
	v_pk_mul_f32 v[14:15], v[102:103], v[166:167]
	s_nop 0
	v_add_f32_e32 v12, v12, v14
	v_add_f32_e32 v12, v12, v15
	s_waitcnt vmcnt(20) lgkmcnt(5)
	v_pk_mul_f32 v[14:15], v[104:105], v[168:169]
	s_nop 0
	v_add_f32_e32 v12, v12, v14
	v_add_f32_e32 v12, v12, v15
	v_pk_mul_f32 v[14:15], v[106:107], v[170:171]
	s_nop 0
	v_add_f32_e32 v12, v12, v14
	v_add_f32_e32 v12, v12, v15
	s_waitcnt vmcnt(16) lgkmcnt(4)
	v_pk_mul_f32 v[14:15], v[108:109], v[172:173]
	s_nop 0
	v_add_f32_e32 v12, v12, v14
	v_add_f32_e32 v12, v12, v15
	v_pk_mul_f32 v[14:15], v[110:111], v[174:175]
	s_nop 0
	v_add_f32_e32 v12, v12, v14
	v_add_f32_e32 v12, v12, v15
	s_waitcnt vmcnt(12) lgkmcnt(3)
	v_fmac_f32_e32 v12, v112, v176
	v_fmac_f32_e32 v12, v113, v177
	v_fmac_f32_e32 v12, v114, v178
	v_fmac_f32_e32 v12, v115, v179
	s_waitcnt vmcnt(8) lgkmcnt(2)
	v_pk_mul_f32 v[14:15], v[116:117], v[180:181]
	s_nop 0
	v_add_f32_e32 v12, v12, v14
	v_add_f32_e32 v12, v12, v15
	v_pk_mul_f32 v[14:15], v[118:119], v[182:183]
	s_nop 0
	v_add_f32_e32 v12, v12, v14
	v_add_f32_e32 v12, v12, v15
	s_waitcnt vmcnt(4) lgkmcnt(1)
	v_pk_mul_f32 v[14:15], v[120:121], v[184:185]
	s_nop 0
	v_add_f32_e32 v12, v12, v14
	v_add_f32_e32 v12, v12, v15
	v_pk_mul_f32 v[14:15], v[122:123], v[186:187]
	s_nop 0
	v_add_f32_e32 v12, v12, v14
	v_add_f32_e32 v12, v12, v15
	s_waitcnt vmcnt(0) lgkmcnt(0)
	v_pk_mul_f32 v[14:15], v[124:125], v[188:189]
	s_nop 0
	v_add_f32_e32 v12, v12, v14
	v_add_f32_e32 v12, v12, v15
	v_pk_mul_f32 v[14:15], v[126:127], v[190:191]
	s_nop 0
	v_add_f32_e32 v12, v12, v14
	v_add_f32_e32 v12, v12, v15
	s_or_b64 exec, exec, s[18:19]

.LBB0_368:
	s_or_b64 exec, exec, s[0:1]
	v_mov_b32_e32 v0, s5
	v_mov_b32_e32 v1, s4
	s_waitcnt lgkmcnt(0)
	s_barrier
	v_readlane_b32 s6, v252, 2
	v_readfirstlane_b32 s0, v1
	v_readfirstlane_b32 s1, v0
	v_mov_b32_e32 v0, s34
	v_mov_b32_e32 v1, s35
	v_readlane_b32 s7, v252, 3
	v_readfirstlane_b32 s4, v0
	v_mov_b32_e32 v0, v192
	s_mov_b32 s7, s53
	s_lshl_b32 s52, s58, 5
	v_add_u32_e32 v128, s6, v0
	v_writelane_b32 v253, s6, 41
	v_readfirstlane_b32 s5, v1
	v_mov_b64_e32 v[4:5], s[0:1]
	v_writelane_b32 v253, s7, 42
	s_lshl_b64 s[6:7], s[52:53], 2
	s_add_u32 s6, s46, s6
	s_addc_u32 s7, s47, s7
	v_writelane_b32 v254, s6, 29
	v_mov_b64_e32 v[2:3], s[4:5]
	s_nop 0
	v_writelane_b32 v254, s7, 30
	s_lshl_b64 s[6:7], s[58:59], 9
	v_writelane_b32 v254, s6, 31
	s_nop 1
	v_writelane_b32 v254, s7, 32
	v_writelane_b32 v254, s44, 33
	s_nop 1
	v_writelane_b32 v254, s45, 34
	v_writelane_b32 v254, s46, 35
	v_writelane_b32 v254, s47, 36
	v_writelane_b32 v254, s58, 37
	s_nop 1
	v_writelane_b32 v254, s59, 38
	s_mov_b32 s100, 1
	s_branch .LBB0_371

.LBB0_371:
	v_cmp_eq_u32_e32 vcc, 0, v128
	s_barrier
	s_and_saveexec_b64 s[0:1], vcc
	s_cbranch_execz .LBB0_375
	s_mov_b64 s[6:7], exec
	v_mbcnt_lo_u32_b32 v0, s6, 0
	v_mbcnt_hi_u32_b32 v0, s7, v0
	v_cmp_eq_u32_e32 vcc, 0, v0
	s_and_saveexec_b64 s[4:5], vcc
	s_cbranch_execz .LBB0_374
	s_cmp_lg_u32 s100, 0
	s_cbranch_scc1 .Lqs3_static
	s_bcnt1_i32_b64 s6, s[6:7]
	v_mov_b32_e32 v1, s6
	v_readlane_b32 s6, v254, 29
	v_readlane_b32 s7, v254, 30
	s_nop 4
	global_atomic_add v1, v195, v1, s[6:7] sc0
	s_waitcnt vmcnt(0)
	v_add_u32_e32 v1, 0x100, v1
	s_branch .Lqs3_join
.Lqs3_static:
	v_readlane_b32 s6, v253, 33
	s_lshr_b32 s6, s6, 3
	v_mov_b32_e32 v1, s6
	s_mov_b32 s100, 0
.Lqs3_join:
.LBB0_374:
	s_or_b64 exec, exec, s[4:5]
	s_waitcnt vmcnt(0)
	v_readfirstlane_b32 s4, v1
	s_nop 1
	v_add_u32_e32 v0, s4, v0
	ds_write_b32 v195, v0 offset:8
.LBB0_375:
	s_or_b64 exec, exec, s[0:1]
	s_waitcnt lgkmcnt(0)
	s_barrier
	ds_read_b32 v0, v195 offset:8
	s_movk_i32 s0, 0x587
	s_waitcnt lgkmcnt(0)
	v_cmp_lt_i32_e64 s[82:83], s0, v0
	v_readfirstlane_b32 s72, v0
	s_and_b64 vcc, exec, s[82:83]
	s_cbranch_vccnz .LBB0_370
	v_readlane_b32 s0, v252, 2
	v_mov_b32_e32 v94, v192
	v_readlane_b32 s1, v252, 3
	s_cmp_gt_i32 s72, 7
	v_readfirstlane_b32 s6, v4
	v_readfirstlane_b32 s7, v5
	v_readfirstlane_b32 s86, v2
	v_readfirstlane_b32 s87, v3
	v_add_u32_e32 v128, s0, v94
	s_mov_b64 s[0:1], -1
	s_cbranch_scc0 .LBB0_1130
	s_cmpk_gt_u32 s72, 0x187
	s_cbranch_scc0 .LBB0_867
	s_sub_i32 s0, 0x587, s72
	s_lshr_b32 s95, s0, 7
	s_lshl_b32 s0, s0, 4
	s_and_b32 s94, s0, 0x7f0
	s_add_u32 s0, s6, 0x1200000
	s_addc_u32 s1, s7, 0
	v_writelane_b32 v254, s0, 39
	s_cmpk_gt_u32 s94, 0xff
	s_nop 0
	v_writelane_b32 v254, s1, 40
	s_mov_b64 s[0:1], -1
	s_cbranch_scc0 .LBB0_855
	s_lshl_b32 s0, s95, 11
	s_lshr_b32 s4, s94, 5
	v_readlane_b32 s11, v253, 45
	v_writelane_b32 v254, s0, 41
	s_cmp_gt_u32 s11, s4
	s_cbranch_scc1 .LBB0_386
	s_add_u32 s0, s6, 0x8200000
	v_readlane_b32 s5, v254, 41
	s_addc_u32 s1, s7, 0
	s_or_b32 s5, s5, s94
	v_bfe_u32 v8, v94, 2, 3
	v_or_b32_e32 v2, s5, v8
	v_ashrrev_i32_e32 v7, 5, v94
	v_mul_u32_u24_e32 v2, 0xd00, v2
	v_lshlrev_b32_e32 v0, 3, v7
	v_lshlrev_b32_e32 v194, 1, v2
	v_lshlrev_b32_e32 v4, 7, v94
	v_ashrrev_i32_e32 v1, 31, v0
	v_lshl_add_u64 v[2:3], s[0:1], 0, v[194:195]
	v_and_b32_e32 v194, 0x180, v4
	v_lshl_add_u64 v[2:3], v[2:3], 0, v[194:195]
	v_lshlrev_b64 v[0:1], 1, v[0:1]
	v_lshl_add_u64 v[2:3], v[2:3], 0, v[0:1]
	global_load_dwordx4 v[32:35], v[2:3], off offset:768
	global_load_dwordx4 v[36:39], v[2:3], off offset:800
	global_load_dwordx4 v[40:43], v[2:3], off offset:832
	global_load_dwordx4 v[44:47], v[2:3], off offset:864
	v_add_u32_e32 v9, s5, v7
	v_mov_b64_e32 v[2:3], s[0:1]
	s_movk_i32 s10, 0x1a00
	s_or_b32 s5, s5, 8
	v_and_b32_e32 v6, 31, v94
	v_or_b32_e32 v4, s5, v8
	v_mul_u32_u24_e32 v4, 0xd00, v4
	v_lshlrev_b32_e32 v4, 1, v4
	v_mov_b32_e32 v5, v195
	v_lshl_add_u64 v[4:5], s[0:1], 0, v[4:5]
	v_lshl_add_u64 v[4:5], v[4:5], 0, v[194:195]
	v_lshl_add_u64 v[4:5], v[4:5], 0, v[0:1]
	v_add_u32_e32 v8, s5, v7
	global_load_dwordx4 v[48:51], v[4:5], off offset:768
	global_load_dwordx4 v[52:55], v[4:5], off offset:800
	global_load_dwordx4 v[56:59], v[4:5], off offset:832
	global_load_dwordx4 v[60:63], v[4:5], off offset:864
	v_mad_i64_i32 v[64:65], s[8:9], v9, s10, v[2:3]
	v_add_u32_e32 v4, 2, v9
	v_mad_i64_i32 v[66:67], s[8:9], v4, s10, v[2:3]
	v_add_u32_e32 v4, 4, v9
	v_mad_i64_i32 v[68:69], s[8:9], v4, s10, v[2:3]
	v_add_u32_e32 v4, 6, v9
	v_mad_i64_i32 v[70:71], s[8:9], v4, s10, v[2:3]
	v_mad_i64_i32 v[72:73], s[8:9], v8, s10, v[2:3]
	v_add_u32_e32 v4, 2, v8
	v_mad_i64_i32 v[74:75], s[8:9], v4, s10, v[2:3]
	v_add_u32_e32 v4, 4, v8
	v_mad_i64_i32 v[76:77], s[8:9], v4, s10, v[2:3]
	v_add_u32_e32 v4, 6, v8
	v_mad_i64_i32 v[78:79], s[8:9], v4, s10, v[2:3]
	global_load_dwordx2 v[64:65], v[64:65], off offset:1408
	global_load_dwordx2 v[66:67], v[66:67], off offset:1408
	global_load_dwordx2 v[68:69], v[68:69], off offset:1408
	global_load_dwordx2 v[70:71], v[70:71], off offset:1408
	global_load_dwordx2 v[72:73], v[72:73], off offset:1408
	global_load_dwordx2 v[74:75], v[74:75], off offset:1408
	global_load_dwordx2 v[76:77], v[76:77], off offset:1408
	global_load_dwordx2 v[78:79], v[78:79], off offset:1408
	s_mov_b32 s8, s11
	s_add_i32 s5, s4, -8
	v_add_u32_e32 v194, s33, v6
	s_movk_i32 s0, 0x2020
	v_mul_lo_u32 v2, v7, s0
	v_lshlrev_b32_e32 v3, 2, v6
	v_readlane_b32 s0, v253, 18
	s_nop 1
	v_add3_u32 v127, v2, v3, s0
	s_lshl_b32 s0, s95, 18
	v_lshlrev_b64 v[2:3], 7, v[194:195]
	s_add_u32 s0, s6, s0
	v_lshl_add_u64 v[0:1], v[2:3], 0, v[0:1]
	s_addc_u32 s1, s7, 0
	v_lshl_add_u64 v[0:1], s[0:1], 0, v[0:1]
	s_mov_b64 s[0:1], 0x600000
	v_lshl_add_u64 v[92:93], v[0:1], 0, s[0:1]
	global_load_dwordx4 v[130:133], v[92:93], off
	global_load_dwordx4 v[134:137], v[92:93], off offset:32
	global_load_dwordx4 v[138:141], v[92:93], off offset:64
	global_load_dwordx4 v[142:145], v[92:93], off offset:96
	s_cmp_gt_i32 s8, s5
	s_cbranch_scc1 .Lidx_p0
	v_add_co_u32_e32 v4, vcc, 0x8000, v92
	s_nop 1
	v_addc_co_u32_e32 v5, vcc, 0, v93, vcc
	global_load_dwordx4 v[146:149], v[4:5], off
	global_load_dwordx4 v[150:153], v[4:5], off offset:32
	global_load_dwordx4 v[154:157], v[4:5], off offset:64
	global_load_dwordx4 v[158:161], v[4:5], off offset:96
.Lidx_p0:
	s_cmp_gt_i32 s8, s5
	s_cbranch_scc1 .Lip_one
	s_waitcnt vmcnt(8)
	s_branch .Lip_w

.Lip_w:
	v_cvt_f32_f16_e32 v95, v64
	v_cvt_f32_f16_sdwa v96, v64 dst_sel:DWORD dst_unused:UNUSED_PAD src0_sel:WORD_1
	v_cvt_f32_f16_e32 v97, v65
	v_cvt_f32_f16_sdwa v98, v65 dst_sel:DWORD dst_unused:UNUSED_PAD src0_sel:WORD_1
	v_cvt_f32_f16_e32 v99, v66
	v_cvt_f32_f16_sdwa v100, v66 dst_sel:DWORD dst_unused:UNUSED_PAD src0_sel:WORD_1
	v_cvt_f32_f16_e32 v101, v67
	v_cvt_f32_f16_sdwa v102, v67 dst_sel:DWORD dst_unused:UNUSED_PAD src0_sel:WORD_1
	v_cvt_f32_f16_e32 v103, v68
	v_cvt_f32_f16_sdwa v104, v68 dst_sel:DWORD dst_unused:UNUSED_PAD src0_sel:WORD_1
	v_cvt_f32_f16_e32 v105, v69
	v_cvt_f32_f16_sdwa v106, v69 dst_sel:DWORD dst_unused:UNUSED_PAD src0_sel:WORD_1
	v_cvt_f32_f16_e32 v107, v70
	v_cvt_f32_f16_sdwa v108, v70 dst_sel:DWORD dst_unused:UNUSED_PAD src0_sel:WORD_1
	v_cvt_f32_f16_e32 v109, v71
	v_cvt_f32_f16_sdwa v110, v71 dst_sel:DWORD dst_unused:UNUSED_PAD src0_sel:WORD_1
	v_cvt_f32_f16_e32 v111, v72
	v_cvt_f32_f16_sdwa v112, v72 dst_sel:DWORD dst_unused:UNUSED_PAD src0_sel:WORD_1
	v_cvt_f32_f16_e32 v113, v73
	v_cvt_f32_f16_sdwa v114, v73 dst_sel:DWORD dst_unused:UNUSED_PAD src0_sel:WORD_1
	v_cvt_f32_f16_e32 v115, v74
	v_cvt_f32_f16_sdwa v116, v74 dst_sel:DWORD dst_unused:UNUSED_PAD src0_sel:WORD_1
	v_cvt_f32_f16_e32 v117, v75
	v_cvt_f32_f16_sdwa v118, v75 dst_sel:DWORD dst_unused:UNUSED_PAD src0_sel:WORD_1
	v_cvt_f32_f16_e32 v119, v76
	v_cvt_f32_f16_sdwa v120, v76 dst_sel:DWORD dst_unused:UNUSED_PAD src0_sel:WORD_1
	v_cvt_f32_f16_e32 v121, v77
	v_cvt_f32_f16_sdwa v122, v77 dst_sel:DWORD dst_unused:UNUSED_PAD src0_sel:WORD_1
	v_cvt_f32_f16_e32 v123, v78
	v_cvt_f32_f16_sdwa v124, v78 dst_sel:DWORD dst_unused:UNUSED_PAD src0_sel:WORD_1
	v_cvt_f32_f16_e32 v125, v79
	v_cvt_f32_f16_sdwa v126, v79 dst_sel:DWORD dst_unused:UNUSED_PAD src0_sel:WORD_1
	s_branch .LBB0_382

.LBB0_1261:
	s_or_b64 exec, exec, s[0:1]
	v_mov_b32_e32 v0, s11
	v_mov_b32_e32 v1, s10
	s_waitcnt lgkmcnt(0)
	s_barrier
	v_readlane_b32 s0, v252, 2
	v_readfirstlane_b32 s76, v1
	v_readfirstlane_b32 s77, v0
	v_mov_b32_e32 v0, s24
	v_mov_b32_e32 v1, s25
	s_lshl_b32 s84, s58, 9
	v_readfirstlane_b32 s82, v0
	v_mov_b32_e32 v0, v192
	v_readfirstlane_b32 s83, v1
	v_readlane_b32 s1, v252, 3
	v_add_u32_e32 v124, s0, v0
	s_mov_b32 s100, 1
	s_branch .LBB0_1264

.LBB0_1264:
	v_cmp_eq_u32_e32 vcc, 0, v124
	s_barrier
	s_and_saveexec_b64 s[0:1], vcc
	s_cbranch_execz .LBB0_1268
	s_mov_b64 s[6:7], exec
	v_mbcnt_lo_u32_b32 v0, s6, 0
	v_mbcnt_hi_u32_b32 v0, s7, v0
	v_cmp_eq_u32_e32 vcc, 0, v0
	s_and_saveexec_b64 s[4:5], vcc
	s_cbranch_execz .LBB0_1267
	s_cmp_lg_u32 s100, 0
	s_cbranch_scc1 .Lqs5_static
	s_bcnt1_i32_b64 s6, s[6:7]
	v_mov_b32_e32 v1, s6
	v_readlane_b32 s6, v254, 29
	v_readlane_b32 s7, v254, 30
	s_nop 4
	global_atomic_add v1, v195, v1, s[6:7] offset:64 sc0
	s_waitcnt vmcnt(0)
	v_add_u32_e32 v1, 0x100, v1
	s_branch .Lqs5_join
